# accumulator rescale in all three mixers: redundant inline full lgkmcnt(0) before the counted waits dropped, 16 multiplies grouped by the read they consume; on top of v_all5
# speedup vs baseline: 1.0014x; 1.0014x over previous
; #define LAS __attribute__((address_space(3)))
; template <int MODE>
; __device__ __forceinline__ void att_tile(LAS unsigned char* lds, int buf, int kv0, int wq0, int r32, int hi, int mapi, const bf16x8 (&qr)[4], f32x16 (&O)[AttCfg<MODE>::NC], float& mrun, float& lsum, LAS float* wsf, bool fixed = false  ) {
;     ...
;     if (!fixed) {
;     if (__any(alpha != 1.0f)) {
;         if (hi == 0) wsf[r32] = alpha;
;         asm volatile("s_waitcnt lgkmcnt(0)" ::: "memory");
; #pragma unroll
;         for (int i = 0; i < 4; ++i) { const f32x4 av = *(const LAS f32x4*)(wsf + 8 * i + 4 * hi);
; #pragma unroll
;             for (int c = 0; c < NC; ++c)
; #pragma unroll
;                 for (int k = 0; k < 4; ++k) O[c][4 * i + k] *= av[k]; }
;         asm volatile("s_waitcnt lgkmcnt(0)" ::: "memory");
;     }
.LBB0_258:
	s_andn2_b64 vcc, exec, s[50:51]
	s_cbranch_vccnz .LBB0_263
	v_cmp_neq_f32_e32 vcc, 1.0, v239
	s_cbranch_vccz .LBB0_263
	s_and_saveexec_b64 s[10:11], s[40:41]
	ds_write_b32 v217, v239
	s_or_b64 exec, exec, s[10:11]
	s_waitcnt lgkmcnt(0)
	ds_read_b128 v[242:245], v216 offset:96
	ds_read_b128 v[246:249], v216 offset:64
	ds_read_b128 v[200:203], v216 offset:32
	ds_read_b128 v[222:225], v216
	s_waitcnt lgkmcnt(3)
	v_pk_mul_f32 v[64:65], v[64:65], v[244:245]
	v_pk_mul_f32 v[62:63], v[62:63], v[242:243]
	v_pk_mul_f32 v[48:49], v[48:49], v[244:245]
	v_pk_mul_f32 v[46:47], v[46:47], v[242:243]
	s_waitcnt lgkmcnt(2)
	v_pk_mul_f32 v[60:61], v[60:61], v[248:249]
	v_pk_mul_f32 v[58:59], v[58:59], v[246:247]
	v_pk_mul_f32 v[44:45], v[44:45], v[248:249]
	v_pk_mul_f32 v[42:43], v[42:43], v[246:247]
	s_waitcnt lgkmcnt(1)
	v_pk_mul_f32 v[56:57], v[56:57], v[202:203]
	v_pk_mul_f32 v[54:55], v[54:55], v[200:201]
	v_pk_mul_f32 v[40:41], v[40:41], v[202:203]
	v_pk_mul_f32 v[38:39], v[38:39], v[200:201]
	s_waitcnt lgkmcnt(0)
	v_pk_mul_f32 v[52:53], v[52:53], v[224:225]
	v_pk_mul_f32 v[50:51], v[50:51], v[222:223]
	v_pk_mul_f32 v[36:37], v[36:37], v[224:225]
	v_pk_mul_f32 v[34:35], v[34:35], v[222:223]
	v_pk_mul_f32 v[32:33], v[32:33], v[244:245]
	v_pk_mul_f32 v[28:29], v[28:29], v[248:249]
	v_pk_mul_f32 v[24:25], v[24:25], v[202:203]
	v_pk_mul_f32 v[20:21], v[20:21], v[224:225]
	v_pk_mul_f32 v[30:31], v[30:31], v[242:243]
	v_pk_mul_f32 v[26:27], v[26:27], v[246:247]
	v_pk_mul_f32 v[22:23], v[22:23], v[200:201]
	v_pk_mul_f32 v[18:19], v[18:19], v[222:223]
	v_pk_mul_f32 v[16:17], v[16:17], v[244:245]
	v_pk_mul_f32 v[12:13], v[12:13], v[248:249]
	v_pk_mul_f32 v[8:9], v[8:9], v[202:203]
	v_pk_mul_f32 v[4:5], v[4:5], v[224:225]
	v_pk_mul_f32 v[14:15], v[14:15], v[242:243]
	v_pk_mul_f32 v[10:11], v[10:11], v[246:247]
	v_pk_mul_f32 v[6:7], v[6:7], v[200:201]
	v_pk_mul_f32 v[2:3], v[2:3], v[222:223]

; #define LAS __attribute__((address_space(3)))
; template <int MODE>
; __device__ __forceinline__ void att_tile(LAS unsigned char* lds, int buf, int kv0, int wq0, int r32, int hi, int mapi, const bf16x8 (&qr)[4], f32x16 (&O)[AttCfg<MODE>::NC], float& mrun, float& lsum, LAS float* wsf, bool fixed = false  ) {
;     ...
;     if (!fixed) {
;     if (__any(alpha != 1.0f)) {
;         if (hi == 0) wsf[r32] = alpha;
;         asm volatile("s_waitcnt lgkmcnt(0)" ::: "memory");
; #pragma unroll
;         for (int i = 0; i < 4; ++i) { const f32x4 av = *(const LAS f32x4*)(wsf + 8 * i + 4 * hi);
; #pragma unroll
;             for (int c = 0; c < NC; ++c)
; #pragma unroll
;                 for (int k = 0; k < 4; ++k) O[c][4 * i + k] *= av[k]; }
;         asm volatile("s_waitcnt lgkmcnt(0)" ::: "memory");
;     }
.LBB0_285:
	s_andn2_b64 vcc, exec, s[50:51]
	s_cbranch_vccnz .LBB0_290
	v_cmp_neq_f32_e32 vcc, 1.0, v239
	s_cbranch_vccz .LBB0_290
	s_and_saveexec_b64 s[10:11], s[40:41]
	ds_write_b32 v217, v239
	s_or_b64 exec, exec, s[10:11]
	s_waitcnt lgkmcnt(0)
	ds_read_b128 v[200:203], v216 offset:96
	ds_read_b128 v[222:225], v216 offset:64
	ds_read_b128 v[242:245], v216 offset:32
	ds_read_b128 v[246:249], v216
	s_waitcnt lgkmcnt(3)
	v_pk_mul_f32 v[64:65], v[64:65], v[202:203]
	v_pk_mul_f32 v[62:63], v[62:63], v[200:201]
	v_pk_mul_f32 v[48:49], v[48:49], v[202:203]
	v_pk_mul_f32 v[46:47], v[46:47], v[200:201]
	s_waitcnt lgkmcnt(2)
	v_pk_mul_f32 v[60:61], v[60:61], v[224:225]
	v_pk_mul_f32 v[58:59], v[58:59], v[222:223]
	v_pk_mul_f32 v[44:45], v[44:45], v[224:225]
	v_pk_mul_f32 v[42:43], v[42:43], v[222:223]
	s_waitcnt lgkmcnt(1)
	v_pk_mul_f32 v[56:57], v[56:57], v[244:245]
	v_pk_mul_f32 v[54:55], v[54:55], v[242:243]
	v_pk_mul_f32 v[40:41], v[40:41], v[244:245]
	v_pk_mul_f32 v[38:39], v[38:39], v[242:243]
	s_waitcnt lgkmcnt(0)
	v_pk_mul_f32 v[52:53], v[52:53], v[248:249]
	v_pk_mul_f32 v[50:51], v[50:51], v[246:247]
	v_pk_mul_f32 v[36:37], v[36:37], v[248:249]
	v_pk_mul_f32 v[34:35], v[34:35], v[246:247]
	v_pk_mul_f32 v[32:33], v[32:33], v[202:203]
	v_pk_mul_f32 v[28:29], v[28:29], v[224:225]
	v_pk_mul_f32 v[24:25], v[24:25], v[244:245]
	v_pk_mul_f32 v[20:21], v[20:21], v[248:249]
	v_pk_mul_f32 v[30:31], v[30:31], v[200:201]
	v_pk_mul_f32 v[26:27], v[26:27], v[222:223]
	v_pk_mul_f32 v[22:23], v[22:23], v[242:243]
	v_pk_mul_f32 v[18:19], v[18:19], v[246:247]
	v_pk_mul_f32 v[16:17], v[16:17], v[202:203]
	v_pk_mul_f32 v[12:13], v[12:13], v[224:225]
	v_pk_mul_f32 v[8:9], v[8:9], v[244:245]
	v_pk_mul_f32 v[4:5], v[4:5], v[248:249]
	v_pk_mul_f32 v[14:15], v[14:15], v[200:201]
	v_pk_mul_f32 v[10:11], v[10:11], v[222:223]
	v_pk_mul_f32 v[6:7], v[6:7], v[242:243]
	v_pk_mul_f32 v[2:3], v[2:3], v[246:247]

; #define LAS __attribute__((address_space(3)))
; template <int MODE>
; __device__ __forceinline__ void att_tile(LAS unsigned char* lds, int buf, int kv0, int wq0, int r32, int hi, int mapi, const bf16x8 (&qr)[4], f32x16 (&O)[AttCfg<MODE>::NC], float& mrun, float& lsum, LAS float* wsf, bool fixed = false  ) {
;     ...
;     if (!fixed) {
;     if (__any(alpha != 1.0f)) {
;         if (hi == 0) wsf[r32] = alpha;
;         asm volatile("s_waitcnt lgkmcnt(0)" ::: "memory");
; #pragma unroll
;         for (int i = 0; i < 4; ++i) { const f32x4 av = *(const LAS f32x4*)(wsf + 8 * i + 4 * hi);
; #pragma unroll
;             for (int c = 0; c < NC; ++c)
; #pragma unroll
;                 for (int k = 0; k < 4; ++k) O[c][4 * i + k] *= av[k]; }
;         asm volatile("s_waitcnt lgkmcnt(0)" ::: "memory");
;     }
.LBB0_348:
	s_andn2_b64 vcc, exec, s[8:9]
	s_cbranch_vccnz .LBB0_353
	v_cmp_neq_f32_e32 vcc, 1.0, v122
	s_cbranch_vccz .LBB0_353
	s_and_saveexec_b64 s[14:15], s[38:39]
	ds_write_b32 v140, v122
	s_or_b64 exec, exec, s[14:15]
	s_waitcnt lgkmcnt(0)
	ds_read_b128 v[154:157], v139 offset:96
	ds_read_b128 v[158:161], v139 offset:64
	ds_read_b128 v[162:165], v139 offset:32
	ds_read_b128 v[166:169], v139
	s_waitcnt lgkmcnt(3)
	v_pk_mul_f32 v[32:33], v[32:33], v[156:157]
	v_pk_mul_f32 v[16:17], v[16:17], v[156:157]
	v_pk_mul_f32 v[30:31], v[30:31], v[154:155]
	v_pk_mul_f32 v[14:15], v[14:15], v[154:155]
	s_waitcnt lgkmcnt(2)
	v_pk_mul_f32 v[28:29], v[28:29], v[160:161]
	v_pk_mul_f32 v[12:13], v[12:13], v[160:161]
	v_pk_mul_f32 v[26:27], v[26:27], v[158:159]
	v_pk_mul_f32 v[10:11], v[10:11], v[158:159]
	s_waitcnt lgkmcnt(1)
	v_pk_mul_f32 v[24:25], v[24:25], v[164:165]
	v_pk_mul_f32 v[8:9], v[8:9], v[164:165]
	v_pk_mul_f32 v[22:23], v[22:23], v[162:163]
	v_pk_mul_f32 v[6:7], v[6:7], v[162:163]
	s_waitcnt lgkmcnt(0)
	v_pk_mul_f32 v[20:21], v[20:21], v[168:169]
	v_pk_mul_f32 v[4:5], v[4:5], v[168:169]
	v_pk_mul_f32 v[18:19], v[18:19], v[166:167]
	v_pk_mul_f32 v[2:3], v[2:3], v[166:167]

; #define LAS __attribute__((address_space(3)))
; __device__ __forceinline__ float xhalf_max(float v) { auto rr = __builtin_amdgcn_permlane32_swap(__float_as_uint(v), __float_as_uint(v), false, false); return fmaxf(__uint_as_float(rr[0]), __uint_as_float(rr[1])); }
; template <int MODE>
; __device__ __forceinline__ void att_tile(LAS unsigned char* lds, int buf, int kv0, int wq0, int r32, int hi, int mapi, const bf16x8 (&qr)[4], f32x16 (&O)[AttCfg<MODE>::NC], float& mrun, float& lsum, LAS float* wsf, bool fixed = false  ) {
;     ...
;     if (!fixed) {
;         float mxa = __builtin_fmaxf(p0[0], p0[1]), mxb = __builtin_fmaxf(p1[0], p1[1]);
; #pragma unroll
;         for (int r = 2; r < 16; r += 2) { mxa = __builtin_fmaxf(__builtin_fmaxf(mxa, p0[r]), p0[r + 1]); mxb = __builtin_fmaxf(__builtin_fmaxf(mxb, p1[r]), p1[r + 1]); }
;         float mx = __builtin_fmaxf(mxa, mxb);
;         mx = xhalf_max(mx);
;         const float mnew = fmaxf(mrun, mx); msafe = (mnew == NEG) ? 0.f : mnew;
;         alpha = __builtin_amdgcn_exp2f(mrun - msafe); mrun = mnew;
;     }
;     float ps = 0.f;
; #pragma unroll
;     for (int r = 0; r < 16; ++r) { p0[r] = __builtin_amdgcn_exp2f(p0[r] - msafe); p1[r] = __builtin_amdgcn_exp2f(p1[r] - msafe); ps += p0[r] + p1[r]; }
;     lsum = lsum * alpha + ps;
;     if (!fixed) {
;     if (__any(alpha != 1.0f)) {
;         if (hi == 0) wsf[r32] = alpha;
;         asm volatile("s_waitcnt lgkmcnt(0)" ::: "memory");
; #pragma unroll
;         for (int i = 0; i < 4; ++i) { const f32x4 av = *(const LAS f32x4*)(wsf + 8 * i + 4 * hi);
; #pragma unroll
;             for (int c = 0; c < NC; ++c)
; #pragma unroll
;                 for (int k = 0; k < 4; ++k) O[c][4 * i + k] *= av[k]; }
;         asm volatile("s_waitcnt lgkmcnt(0)" ::: "memory");
;     }
.LBB0_415:
	s_nop 4
	v_max_f32_e32 v139, v35, v35
	v_max_f32_e32 v142, v34, v34
	v_max_f32_e32 v139, v142, v139
	v_max3_f32 v142, v50, v51, v52
	v_max3_f32 v139, v139, v36, v37
	v_max3_f32 v142, v142, v53, v54
	v_max3_f32 v139, v139, v38, v39
	v_max3_f32 v142, v142, v55, v56
	v_max3_f32 v139, v139, v40, v41
	v_max3_f32 v142, v142, v57, v58
	v_max3_f32 v139, v139, v42, v43
	v_max3_f32 v142, v142, v59, v60
	v_max3_f32 v139, v139, v44, v45
	v_max3_f32 v142, v142, v61, v62
	v_max3_f32 v139, v139, v46, v47
	v_max3_f32 v142, v142, v63, v64
	v_max3_f32 v139, v139, v48, v49
	v_max3_f32 v139, v142, v65, v139
	v_mov_b32_e32 v142, v139
	s_nop 1
	v_permlane32_swap_b32_e32 v139, v142
	v_max3_f32 v139, v138, v139, v142
	v_cmp_neq_f32_e32 vcc, s66, v139
	s_nop 1
	v_cndmask_b32_e32 v142, 0, v139, vcc
	v_sub_f32_e32 v138, v138, v142
	v_exp_f32_e32 v138, v138
	s_nop 0
	v_cmp_neq_f32_e32 vcc, 1.0, v138
	s_cbranch_vccz .LBB0_419
	s_and_saveexec_b64 s[10:11], s[36:37]
	ds_write_b32 v122, v138
	s_or_b64 exec, exec, s[10:11]
	s_waitcnt lgkmcnt(0)
	ds_read_b128 v[144:147], v131 offset:96
	ds_read_b128 v[148:151], v131 offset:64
	ds_read_b128 v[152:155], v131 offset:32
	ds_read_b128 v[156:159], v131
	s_waitcnt lgkmcnt(3)
	v_pk_mul_f32 v[16:17], v[16:17], v[146:147]
	v_pk_mul_f32 v[32:33], v[32:33], v[146:147]
	v_pk_mul_f32 v[14:15], v[14:15], v[144:145]
	v_pk_mul_f32 v[30:31], v[30:31], v[144:145]
	s_waitcnt lgkmcnt(2)
	v_pk_mul_f32 v[12:13], v[12:13], v[150:151]
	v_pk_mul_f32 v[28:29], v[28:29], v[150:151]
	v_pk_mul_f32 v[10:11], v[10:11], v[148:149]
	v_pk_mul_f32 v[26:27], v[26:27], v[148:149]
	s_waitcnt lgkmcnt(1)
	v_pk_mul_f32 v[8:9], v[8:9], v[154:155]
	v_pk_mul_f32 v[24:25], v[24:25], v[154:155]
	v_pk_mul_f32 v[6:7], v[6:7], v[152:153]
	v_pk_mul_f32 v[22:23], v[22:23], v[152:153]
	s_waitcnt lgkmcnt(0)
	v_pk_mul_f32 v[4:5], v[4:5], v[158:159]
	v_pk_mul_f32 v[20:21], v[20:21], v[158:159]
	v_pk_mul_f32 v[2:3], v[2:3], v[156:157]
	v_pk_mul_f32 v[18:19], v[18:19], v[156:157]

; #define LAS __attribute__((address_space(3)))
; __device__ __forceinline__ float xhalf_max(float v) { auto rr = __builtin_amdgcn_permlane32_swap(__float_as_uint(v), __float_as_uint(v), false, false); return fmaxf(__uint_as_float(rr[0]), __uint_as_float(rr[1])); }
; template <int MODE>
; __device__ __forceinline__ void att_tile(LAS unsigned char* lds, int buf, int kv0, int wq0, int r32, int hi, int mapi, const bf16x8 (&qr)[4], f32x16 (&O)[AttCfg<MODE>::NC], float& mrun, float& lsum, LAS float* wsf, bool fixed = false  ) {
;     ...
;     if (!fixed) {
;         float mxa = __builtin_fmaxf(p0[0], p0[1]), mxb = __builtin_fmaxf(p1[0], p1[1]);
; #pragma unroll
;         for (int r = 2; r < 16; r += 2) { mxa = __builtin_fmaxf(__builtin_fmaxf(mxa, p0[r]), p0[r + 1]); mxb = __builtin_fmaxf(__builtin_fmaxf(mxb, p1[r]), p1[r + 1]); }
;         float mx = __builtin_fmaxf(mxa, mxb);
;         mx = xhalf_max(mx);
;         const float mnew = fmaxf(mrun, mx); msafe = (mnew == NEG) ? 0.f : mnew;
;         alpha = __builtin_amdgcn_exp2f(mrun - msafe); mrun = mnew;
;     }
;     float ps = 0.f;
; #pragma unroll
;     for (int r = 0; r < 16; ++r) { p0[r] = __builtin_amdgcn_exp2f(p0[r] - msafe); p1[r] = __builtin_amdgcn_exp2f(p1[r] - msafe); ps += p0[r] + p1[r]; }
;     lsum = lsum * alpha + ps;
;     if (!fixed) {
;     if (__any(alpha != 1.0f)) {
;         if (hi == 0) wsf[r32] = alpha;
;         asm volatile("s_waitcnt lgkmcnt(0)" ::: "memory");
; #pragma unroll
;         for (int i = 0; i < 4; ++i) { const f32x4 av = *(const LAS f32x4*)(wsf + 8 * i + 4 * hi);
; #pragma unroll
;             for (int c = 0; c < NC; ++c)
; #pragma unroll
;                 for (int k = 0; k < 4; ++k) O[c][4 * i + k] *= av[k]; }
;         asm volatile("s_waitcnt lgkmcnt(0)" ::: "memory");
;     }
.LBB0_430:
	s_nop 4
	v_max_f32_e32 v138, v35, v35
	v_max_f32_e32 v142, v34, v34
	v_max_f32_e32 v138, v142, v138
	v_max3_f32 v142, v50, v51, v52
	v_max3_f32 v138, v138, v36, v37
	v_max3_f32 v142, v142, v53, v54
	v_max3_f32 v138, v138, v38, v39
	v_max3_f32 v142, v142, v55, v56
	v_max3_f32 v138, v138, v40, v41
	v_max3_f32 v142, v142, v57, v58
	v_max3_f32 v138, v138, v42, v43
	v_max3_f32 v142, v142, v59, v60
	v_max3_f32 v138, v138, v44, v45
	v_max3_f32 v142, v142, v61, v62
	v_max3_f32 v138, v138, v46, v47
	v_max3_f32 v142, v142, v63, v64
	v_max3_f32 v138, v138, v48, v49
	v_max3_f32 v138, v142, v65, v138
	v_mov_b32_e32 v142, v138
	s_nop 1
	v_permlane32_swap_b32_e32 v138, v142
	v_max3_f32 v138, v139, v138, v142
	v_cmp_neq_f32_e32 vcc, s66, v138
	s_nop 1
	v_cndmask_b32_e32 v142, 0, v138, vcc
	v_sub_f32_e32 v139, v139, v142
	v_exp_f32_e32 v139, v139
	s_nop 0
	v_cmp_neq_f32_e32 vcc, 1.0, v139
	s_cbranch_vccz .LBB0_434
	s_and_saveexec_b64 s[10:11], s[36:37]
	ds_write_b32 v122, v139
	s_or_b64 exec, exec, s[10:11]
	s_waitcnt lgkmcnt(0)
	ds_read_b128 v[144:147], v131 offset:96
	ds_read_b128 v[148:151], v131 offset:64
	ds_read_b128 v[152:155], v131 offset:32
	ds_read_b128 v[156:159], v131
	s_waitcnt lgkmcnt(3)
	v_pk_mul_f32 v[16:17], v[16:17], v[146:147]
	v_pk_mul_f32 v[32:33], v[32:33], v[146:147]
	v_pk_mul_f32 v[14:15], v[14:15], v[144:145]
	v_pk_mul_f32 v[30:31], v[30:31], v[144:145]
	s_waitcnt lgkmcnt(2)
	v_pk_mul_f32 v[12:13], v[12:13], v[150:151]
	v_pk_mul_f32 v[28:29], v[28:29], v[150:151]
	v_pk_mul_f32 v[10:11], v[10:11], v[148:149]
	v_pk_mul_f32 v[26:27], v[26:27], v[148:149]
	s_waitcnt lgkmcnt(1)
	v_pk_mul_f32 v[8:9], v[8:9], v[154:155]
	v_pk_mul_f32 v[24:25], v[24:25], v[154:155]
	v_pk_mul_f32 v[6:7], v[6:7], v[152:153]
	v_pk_mul_f32 v[22:23], v[22:23], v[152:153]
	s_waitcnt lgkmcnt(0)
	v_pk_mul_f32 v[4:5], v[4:5], v[158:159]
	v_pk_mul_f32 v[20:21], v[20:21], v[158:159]
	v_pk_mul_f32 v[2:3], v[2:3], v[156:157]
	v_pk_mul_f32 v[18:19], v[18:19], v[156:157]
